# phase 3: alternate CUs run their pooling items before their gMLP items so the streaming and compute-heavier halves overlap across the chip
# speedup vs baseline: 1.0041x; 1.0041x over previous
.LBB0_330:
	s_or_b64 exec, exec, s[0:1]
	s_waitcnt lgkmcnt(0)
	v_mov_b32_e32 v0, v254
	s_cmpk_gt_i32 s2, 0x7ff
	s_barrier
	s_cbranch_scc1 .LBB0_409
	v_bfe_u32 v6, v0, 5, 1
	v_ashrrev_i32_e32 v187, 5, v0
	v_lshlrev_b32_e32 v9, 9, v0
	v_lshlrev_b32_e32 v18, 3, v6
	s_movk_i32 s6, 0xff00
	v_lshlrev_b32_e32 v23, 2, v187
	v_bfe_u32 v1, v0, 2, 2
	v_lshrrev_b32_e32 v2, 3, v0
	v_bfe_u32 v4, v0, 1, 1
	v_and_b32_e32 v7, 31, v0
	v_bfe_u32 v149, v0, 6, 2
	v_ashrrev_i32_e32 v8, 8, v0
	v_and_b32_e32 v9, 0x2000, v9
	v_and_b32_e32 v10, 15, v0
	v_bfe_u32 v11, v187, 2, 2
	v_ashrrev_i32_e32 v12, 2, v0
	v_lshlrev_b32_e32 v13, 7, v0
	v_lshlrev_b32_e32 v14, 12, v0
	v_lshlrev_b32_e32 v15, 3, v0
	v_and_b32_e32 v17, 12, v0
	v_and_or_b32 v19, v0, s6, v18
	v_lshlrev_b32_e32 v0, 9, v187
	v_and_b32_e32 v23, 12, v23
	v_add_u32_e32 v9, 0, v9
	v_and_b32_e32 v21, 0xffffc000, v0
	v_lshlrev_b32_e32 v22, 8, v187
	v_bitop3_b32 v23, v23, v10, v11 bitop3:0x36
	v_add_u32_e32 v21, v9, v21
	v_and_b32_e32 v22, 0x1f00, v22
	v_lshlrev_b32_e32 v23, 4, v23
	v_add3_u32 v189, v21, v23, v22
	v_add_u32_e32 v21, 16, v187
	v_lshlrev_b32_e32 v24, 9, v21
	v_and_b32_e32 v25, 31, v21
	v_lshlrev_b32_e32 v21, 2, v21
	v_and_b32_e32 v21, 12, v21
	v_and_b32_e32 v24, 0xffffc000, v24
	v_bitop3_b32 v21, v21, v10, v11 bitop3:0x36
	v_add_u32_e32 v24, v9, v24
	v_lshlrev_b32_e32 v25, 8, v25
	v_lshlrev_b32_e32 v21, 4, v21
	v_add3_u32 v191, v24, v21, v25
	v_add_u32_e32 v21, 0x4000, v0
	v_and_b32_e32 v21, 0xffffc000, v21
	v_add_u32_e32 v21, v9, v21
	v_add3_u32 v192, v21, v23, v22
	v_add_u32_e32 v21, 48, v187
	v_lshlrev_b32_e32 v24, 9, v21
	v_and_b32_e32 v25, 31, v21
	v_lshlrev_b32_e32 v21, 2, v21
	v_and_b32_e32 v21, 12, v21
	v_and_b32_e32 v24, 0xffffc000, v24
	v_bitop3_b32 v21, v21, v10, v11 bitop3:0x36
	v_add_u32_e32 v24, v9, v24
	v_lshlrev_b32_e32 v25, 8, v25
	v_lshlrev_b32_e32 v21, 4, v21
	v_add3_u32 v193, v24, v21, v25
	v_add_u32_e32 v21, 0x8000, v0
	v_and_b32_e32 v21, 0xffffc000, v21
	v_add_u32_e32 v21, v9, v21
	v_add3_u32 v194, v21, v23, v22
	v_add_u32_e32 v21, 0x50, v187
	v_lshlrev_b32_e32 v24, 9, v21
	v_and_b32_e32 v25, 31, v21
	v_lshlrev_b32_e32 v21, 2, v21
	v_add_u32_e32 v0, 0xc000, v0
	v_and_b32_e32 v21, 12, v21
	v_and_b32_e32 v0, 0xffffc000, v0
	v_and_b32_e32 v24, 0xffffc000, v24
	v_bitop3_b32 v21, v21, v10, v11 bitop3:0x36
	v_add_u32_e32 v0, v9, v0
	v_add_u32_e32 v24, v9, v24
	v_lshlrev_b32_e32 v25, 8, v25
	v_lshlrev_b32_e32 v21, 4, v21
	v_add3_u32 v196, v0, v23, v22
	v_add_u32_e32 v0, 0x70, v187
	v_add3_u32 v195, v24, v21, v25
	v_lshlrev_b32_e32 v21, 9, v0
	v_and_b32_e32 v21, 0xffffc000, v21
	v_add_u32_e32 v9, v9, v21
	v_and_b32_e32 v21, 31, v0
	v_lshlrev_b32_e32 v0, 2, v0
	v_and_b32_e32 v0, 12, v0
	v_bitop3_b32 v0, v0, v10, v11 bitop3:0x36
	v_and_b32_e32 v15, 8, v15
	v_lshlrev_b32_e32 v16, 8, v12
	v_bfe_u32 v12, v12, 2, 2
	v_lshlrev_b32_e32 v21, 8, v21
	v_lshlrev_b32_e32 v0, 4, v0
	v_add3_u32 v197, v9, v0, v21
	v_bitop3_b32 v0, v17, v15, v12 bitop3:0x36
	v_lshlrev_b32_e32 v9, 4, v0
	v_or_b32_e32 v0, 1, v15
	v_bitop3_b32 v0, v17, v0, v12 bitop3:0x36
	v_lshlrev_b32_e32 v10, 4, v0
	v_or_b32_e32 v0, 2, v15
	v_bitop3_b32 v0, v17, v0, v12 bitop3:0x36
	v_lshlrev_b32_e32 v11, 4, v0
	v_or_b32_e32 v0, 3, v15
	v_bitop3_b32 v0, v17, v0, v12 bitop3:0x36
	v_lshlrev_b32_e32 v21, 4, v0
	v_or_b32_e32 v0, 4, v15
	v_and_b32_e32 v13, 0xffffc000, v13
	v_bitop3_b32 v0, v17, v0, v12 bitop3:0x36
	v_add_u32_e32 v13, 0, v13
	v_and_b32_e32 v14, 0x2000, v14
	v_and_b32_e32 v16, 0x1f00, v16
	v_lshlrev_b32_e32 v22, 4, v0
	v_or_b32_e32 v0, 5, v15
	v_add3_u32 v13, v13, v14, v16
	v_lshlrev_b32_e32 v14, 13, v8
	v_lshlrev_b32_e32 v16, 11, v6
	v_bitop3_b32 v0, v17, v0, v12 bitop3:0x36
	v_add3_u32 v14, 0, v14, v16
	v_lshlrev_b32_e32 v16, 8, v1
	v_lshlrev_b32_e32 v23, 4, v0
	v_or_b32_e32 v0, 6, v15
	v_and_b32_e32 v3, 2, v2
	v_add3_u32 v14, v14, v16, v15
	v_lshlrev_b32_e32 v16, 1, v6
	v_bitop3_b32 v0, v17, v0, v12 bitop3:0x36
	s_add_u32 s8, s28, 0x80000
	v_or_b32_e32 v5, v3, v4
	v_lshlrev_b32_e32 v148, 3, v7
	v_bitop3_b32 v3, v3, v16, v4 bitop3:0x36
	v_lshlrev_b32_e32 v4, 7, v8
	v_lshlrev_b32_e32 v24, 4, v0
	v_or_b32_e32 v0, 7, v15
	s_addc_u32 s9, s29, 0
	v_lshl_or_b32 v2, v149, 8, v148
	v_mov_b32_e32 v151, 0
	v_lshlrev_b32_e32 v150, 4, v7
	v_bitop3_b32 v16, v16, v5, 1 bitop3:0x36
	v_ashrrev_i32_e32 v5, 31, v4
	s_add_i32 s0, 0, 0x10000
	v_bitop3_b32 v0, v17, v0, v12 bitop3:0x36
	v_lshl_add_u64 v[152:153], s[70:71], 0, v[150:151]
	v_add_u32_e32 v20, s0, v150
	v_lshlrev_b32_e32 v12, 4, v0
	v_lshlrev_b32_e32 v200, 6, v1
	v_lshlrev_b32_e32 v150, 2, v2
	v_lshlrev_b64 v[0:1], 2, v[4:5]
	v_lshl_or_b32 v188, v149, 5, v7
	s_movk_i32 s1, 0x210
	v_mov_b32_e32 v7, s0
	v_lshl_add_u64 v[154:155], s[62:63], 0, v[150:151]
	v_lshl_add_u64 v[156:157], s[64:65], 0, v[150:151]
	v_lshl_add_u64 v[4:5], s[52:53], 0, v[0:1]
	v_lshlrev_b32_e32 v150, 4, v6
	v_lshl_add_u64 v[0:1], s[54:55], 0, v[0:1]
	v_mad_u32_u24 v7, v188, s1, v7
	v_lshl_add_u32 v198, v3, 4, v14
	v_mul_lo_u32 v3, v187, s1
	v_lshl_add_u64 v[158:159], v[4:5], 0, v[150:151]
	v_lshl_add_u64 v[160:161], v[0:1], 0, v[150:151]
	v_lshl_or_b32 v0, v149, 4, v6
	v_lshlrev_b32_e32 v150, 1, v2
	s_mov_b32 s13, 0
	v_cmp_lt_u32_e64 s[4:5], 1, v149
	s_mov_b32 s3, 0x10000
	s_mov_b32 s51, 0x8000
	s_mov_b32 s66, 0xc000
	v_lshl_add_u32 v199, v16, 4, v14
	v_xor_b32_e32 v201, 64, v200
	v_xor_b32_e32 v202, 0x80, v200
	v_xor_b32_e32 v203, 0xc0, v200
	v_lshl_add_u64 v[162:163], s[18:19], 0, v[150:151]
	v_lshl_or_b32 v204, v8, 4, v18
	s_lshl_b32 s53, s2, 5
	s_lshl_b32 s55, s30, 5
	s_movk_i32 s62, 0x2800
	v_lshlrev_b32_e32 v164, 1, v2
	s_mov_b64 s[24:25], 0x1800
	s_mov_b32 s63, 0xf000
	s_mov_b32 s64, 0x11000
	s_movk_i32 s65, 0x3000
	s_mov_b32 s67, 0xd000
	s_mov_b32 s70, 0x12000
	s_mov_b32 s50, 0x3e000000
	s_mov_b32 s52, 0x3e800000
	v_lshlrev_b32_e32 v205, 9, v0
	s_movk_i32 s71, 0x1000
	s_mov_b32 s72, 0x28000
	s_mov_b32 s73, 0x50000
	s_mov_b32 s74, 0x78000
	s_mov_b32 s75, 0xa0000
	s_mov_b32 s76, 0xc8000
	s_mov_b32 s77, 0xf0000
	s_mov_b32 s78, 0x118000
	v_add_u32_e32 v206, v13, v9
	v_add_u32_e32 v207, v13, v10
	v_add_u32_e32 v208, v13, v11
	v_add_u32_e32 v209, v13, v24
	v_add_u32_e32 v210, v13, v21
	v_add_u32_e32 v211, v13, v22
	v_add_u32_e32 v212, v13, v23
	v_add_u32_e32 v213, v13, v12
	s_mov_b32 s54, 0x3b800000
	s_mov_b32 s79, 0x800000
	s_mov_b32 s80, 0x29000
	s_mov_b32 s81, 0x51000
	s_mov_b32 s82, 0x79000
	s_mov_b32 s83, 0xa1000
	s_mov_b32 s84, 0xc9000
	s_mov_b32 s85, 0xf1000
	s_mov_b32 s86, 0x119000
	v_add_u32_e32 v214, v7, v19
	v_add_u32_e32 v215, v20, v3
	s_mov_b32 s87, 0x20000
	s_mov_b32 s88, 0x30000
	s_mov_b32 s89, 0x40000
	s_mov_b32 s90, 0x60000
	v_mbcnt_hi_u32_b32 v216, -1, v186
	s_mov_b32 s91, s2
	s_mov_b32 s98, 0
	s_mov_b32 s99, 0
	s_cmp_lg_u32 s30, 0x100
	s_cbranch_scc1 .LBB0_334
	s_bitcmp0_b32 s2, 3
	s_cbranch_scc1 .LBB0_334
	s_mov_b32 s98, 1
	s_mov_b32 s99, 1
	s_add_i32 s91, s91, 0x400
	s_add_i32 s53, s53, 0x8000
	s_branch .LBB0_334

.LBB0_333:
	s_add_i32 s91, s91, s30
	s_add_i32 s53, s53, s55
	s_cmpk_lt_i32 s91, 0x800
	s_cbranch_scc1 .Lp3_cont
	s_cmp_eq_u32 s98, 0
	s_cbranch_scc1 .LBB0_409
	s_mov_b32 s98, 0
	s_sub_i32 s91, s91, 0x800
	s_sub_i32 s53, s53, 0x10000
.Lp3_cont:
	s_cmp_eq_u32 s99, 0
	s_cbranch_scc1 .LBB0_334
	s_cmp_lg_u32 s98, 0
	s_cbranch_scc1 .LBB0_334
	s_cmpk_lt_i32 s91, 0x400
	s_cbranch_scc0 .LBB0_409
